# MLA next-unit prefetch: computing waves request the next query fragments right behind their last QK MFMA in the last iteration
# baseline (speedup 1.0000x reference)
;     ...
;     bf16x8 qf[KS];
; #pragma unroll
;     for (int ks = 0; ks < KS; ++ks) {
;         if (ks < 4) qf[ks] = *(const bf16x8*)(qa + (size_t)myq * ldqa + ks * 16 + h * 8);
;         else qf[ks] = *(const bf16x8*)(qb + (size_t)myq * ldqb + (ks - 4) * 16 + h * 8);
;     }
; DI void phase3(const Params& p, unsigned char* smem, int tid, int cidx) {
;     ...
;         for (int r = 0; r < 2; ++r) {
;             const int bh = (r * 4 + s4) * 8 + xcd, b = bh >> 4, hd = bh & 15;
;             const size_t t0 = (size_t)b * L;
;             for (int half = 0; half < 2; ++half) {
;                 const int qi = half == 0 ? 15 - j8 : j8;
;                 bf16_t* qn = (bf16_t*)(ws + OFF_QN) + t0 * 1024 + hd * 64;
;                 attn_unit<96, false>(qn, 1024, (const bf16_t*)(ws + OFF_QPE) + t0 * 512 + hd * 32, 512,
;                                      (const bf16_t*)(ob + OUT_KM) + t0 * 1536 + hd * 96, 1536,
;                                      (const bf16_t*)(ws + OFF_VMT) + (size_t)(b * NH + hd) * 64 * LP, nullptr, qn, 1024, qi, lds, tid);
.Lmp_qe:
	s_and_b64 vcc, exec, s[48:49]
	s_cbranch_vccnz .Lmp_qe_r
	v_add3_u32 v102, v137, s58, 16
	v_add_u32_e32 v102, v102, v208
	v_ashrrev_i32_e32 v103, 31, v102
	v_lshlrev_b64 v[104:105], 10, v[102:103]
	v_lshlrev_b64 v[102:103], 11, v[102:103]
	v_lshl_add_u64 v[102:103], v[160:161], 0, v[102:103]
	global_load_dwordx4 v[66:69], v[102:103], off
	global_load_dwordx4 v[70:73], v[102:103], off offset:32
	global_load_dwordx4 v[74:77], v[102:103], off offset:64
	global_load_dwordx4 v[78:81], v[102:103], off offset:96
	v_lshl_add_u64 v[104:105], v[170:171], 0, v[104:105]
	global_load_dwordx4 v[82:85], v[104:105], off
	global_load_dwordx4 v[86:89], v[104:105], off offset:32
	s_branch .Lmp_qe_back
.Lmp_qe_r:
	s_and_b64 vcc, exec, s[46:47]
	s_cbranch_vccnz .Lmp_qe_back
	s_lshl_b64 s[98:99], s[100:101], 11
	s_add_u32 s98, s17, s98
	s_addc_u32 s99, s33, s99
	v_lshlrev_b32_e32 v106, 1, v152
	v_mov_b32_e32 v107, 0
	v_lshl_add_u64 v[106:107], s[98:99], 0, v[106:107]
	v_add3_u32 v102, v137, s59, 16
	v_add_u32_e32 v102, v102, v208
	v_ashrrev_i32_e32 v103, 31, v102
	v_lshlrev_b64 v[104:105], 10, v[102:103]
	v_lshlrev_b64 v[102:103], 11, v[102:103]
	v_lshl_add_u64 v[102:103], v[106:107], 0, v[102:103]
	global_load_dwordx4 v[66:69], v[102:103], off
	global_load_dwordx4 v[70:73], v[102:103], off offset:32
	global_load_dwordx4 v[74:77], v[102:103], off offset:64
	global_load_dwordx4 v[78:81], v[102:103], off offset:96
	s_lshl_b64 s[98:99], s[100:101], 10
	v_lshl_add_u64 v[106:107], v[148:149], 0, s[98:99]
	v_lshl_add_u64 v[104:105], v[106:107], 0, v[104:105]
	global_load_dwordx4 v[82:85], v[104:105], off
	global_load_dwordx4 v[86:89], v[104:105], off offset:32
	s_branch .Lmp_qe_back

;     ...
;             bf16x8 kf[KS][2];
; #pragma unroll
;             for (int ks = 0; ks < KS; ++ks)
; #pragma unroll
;                 for (int t2 = 0; t2 < 2; ++t2) kf[ks][t2] = *(const bf16x8*)(kb + (t2 * 32 + ln) * KROW + ks * 32 + h * 16);
;             __builtin_amdgcn_sched_barrier(0);
; #pragma unroll
;             for (int ks = 0; ks < KS; ++ks)
; #pragma unroll
;                 for (int t2 = 0; t2 < 2; ++t2) s[t2] = __builtin_amdgcn_mfma_f32_32x32x16_bf16(kf[ks][t2], qf[ks], s[t2], 0, 0, 0);
;             __builtin_amdgcn_sched_barrier(0);
;             u32x2 vf[4][2][2];
; #pragma unroll
;             for (int kk = 0; kk < 4; ++kk)
; #pragma unroll
;                 for (int d = 0; d < 2; ++d) {
;                     const unsigned char* va = vb + (d * 32 + ln) * VROW + (16 * kk + 4 * h) * 2;
;                     vf[kk][d][0] = *(const u32x2*)va; vf[kk][d][1] = *(const u32x2*)(va + 16);
;                 }
;             __builtin_amdgcn_sched_barrier(0);
;             if (64 * j + 63 > qw0) {
;                 const int thr = myq - 64 * j - 4 * h;
; #pragma unroll
;                 for (int t2 = 0; t2 < 2; ++t2)
; #pragma unroll
;                     for (int r = 0; r < 16; ++r) { if (((r & 3) + 8 * (r >> 2) + 32 * t2) > thr) s[t2][r] = -INFINITY; }
;             }
.LBB0_754:
	s_add_i32 s8, s42, 64
	s_and_b32 s61, s60, 1
	v_cmp_le_i32_e32 vcc, s8, v218
	s_and_saveexec_b64 s[66:67], vcc
	s_cbranch_execz .LBB0_760
	s_mul_i32 s8, s61, 0x5700
	s_add_i32 s8, s8, 0
	v_add3_u32 v1, s8, v150, v200
	ds_read_b128 v[34:37], v1 offset:2048
	ds_read_b128 v[102:105], v1 offset:2080
	ds_read_b128 v[38:41], v1 offset:8704
	ds_read_b128 v[106:109], v1 offset:8736
	ds_read_b128 v[110:113], v1 offset:2112
	ds_read_b128 v[114:117], v1 offset:2144
	ds_read_b128 v[118:121], v1 offset:8768
	ds_read_b128 v[122:125], v1 offset:8800
	ds_read_b128 v[126:129], v1 offset:2176
	ds_read_b128 v[130:133], v1 offset:2208
	ds_read_b128 v[222:225], v1 offset:8832
	ds_read_b128 v[226:229], v1 offset:8864
	s_waitcnt lgkmcnt(11)
	v_mfma_f32_32x32x16_bf16 v[50:65], v[34:37], v[66:69], v[230:245]
	s_waitcnt lgkmcnt(9)
	v_mfma_f32_32x32x16_bf16 v[34:49], v[38:41], v[66:69], v[230:245]
	v_mfma_f32_32x32x16_bf16 v[50:65], v[102:105], v[70:73], v[50:65]
	s_waitcnt lgkmcnt(8)
	v_mfma_f32_32x32x16_bf16 v[34:49], v[106:109], v[70:73], v[34:49]
	s_waitcnt lgkmcnt(7)
	v_mfma_f32_32x32x16_bf16 v[50:65], v[110:113], v[74:77], v[50:65]
	s_waitcnt lgkmcnt(5)
	v_mfma_f32_32x32x16_bf16 v[34:49], v[118:121], v[74:77], v[34:49]
	v_mfma_f32_32x32x16_bf16 v[50:65], v[114:117], v[78:81], v[50:65]
	s_waitcnt lgkmcnt(4)
	v_mfma_f32_32x32x16_bf16 v[34:49], v[122:125], v[78:81], v[34:49]
	s_waitcnt lgkmcnt(3)
	v_mfma_f32_32x32x16_bf16 v[50:65], v[126:129], v[82:85], v[50:65]
	s_waitcnt lgkmcnt(1)
	v_mfma_f32_32x32x16_bf16 v[34:49], v[222:225], v[82:85], v[34:49]
	v_mfma_f32_32x32x16_bf16 v[50:65], v[130:133], v[86:89], v[50:65]
	s_waitcnt lgkmcnt(0)
	v_mfma_f32_32x32x16_bf16 v[34:49], v[226:229], v[86:89], v[34:49]
	s_andn2_b64 vcc, exec, s[64:65]
	s_cbranch_vccnz .Lmp_qe
.Lmp_qe_back:
	v_add3_u32 v1, s8, v152, v181
	v_add_u32_e32 v102, 0x3800, v1
	v_add_u32_e32 v1, 0x4800, v1
	ds_read2_b64 v[130:133], v102 offset0:128 offset1:130
	ds_read2_b64 v[122:125], v102 offset0:132 offset1:134
	ds_read2_b64 v[126:129], v1 offset0:160 offset1:162
	ds_read2_b64 v[118:121], v1 offset0:164 offset1:166
	ds_read2_b64 v[114:117], v102 offset0:136 offset1:138
	ds_read2_b64 v[110:113], v1 offset0:168 offset1:170
	ds_read2_b64 v[106:109], v102 offset0:140 offset1:142
	ds_read2_b64 v[102:105], v1 offset0:172 offset1:174
	s_add_i32 s8, s42, 0x7f
	v_cmp_gt_i32_e32 vcc, s8, v159
	s_and_saveexec_b64 s[68:69], vcc
	s_cbranch_execz .LBB0_757
	v_cmp_gt_i32_e32 vcc, 0, v219
	v_cmp_gt_i32_e64 s[8:9], 1, v219
	s_and_b64 vcc, s[8:9], vcc
	v_cndmask_b32_e32 v50, v50, v217, vcc
	v_cmp_lt_i32_e32 vcc, 1, v219
	v_cmp_gt_i32_e64 s[38:39], 58, v219
	v_cmp_gt_i32_e64 s[40:41], 59, v219
	v_cndmask_b32_e32 v52, v217, v52, vcc
	v_cmp_lt_i32_e32 vcc, 2, v219
	v_cmp_gt_i32_e64 s[36:37], 57, v219
	s_and_b64 s[38:39], s[40:41], s[38:39]
	v_cndmask_b32_e32 v53, v217, v53, vcc
	v_cmp_lt_i32_e32 vcc, 7, v219
	v_cmp_gt_i32_e64 s[34:35], 56, v219
	s_and_b64 s[36:37], s[38:39], s[36:37]
	v_cndmask_b32_e32 v54, v217, v54, vcc
	v_cmp_lt_i32_e32 vcc, 8, v219
	v_cmp_gt_i32_e64 s[30:31], 51, v219
	s_and_b64 s[34:35], s[36:37], s[34:35]
	v_cndmask_b32_e32 v55, v217, v55, vcc
	v_cmp_lt_i32_e32 vcc, 9, v219
	v_cmp_gt_i32_e64 s[28:29], 50, v219
	s_and_b64 s[30:31], s[34:35], s[30:31]
	v_cndmask_b32_e32 v56, v217, v56, vcc
	v_cmp_lt_i32_e32 vcc, 10, v219
	v_cmp_gt_i32_e64 s[26:27], 49, v219
	s_and_b64 s[28:29], s[30:31], s[28:29]
	v_cndmask_b32_e32 v57, v217, v57, vcc
	v_cmp_lt_i32_e32 vcc, 15, v219
	v_cmp_gt_i32_e64 s[24:25], 48, v219
	s_and_b64 s[26:27], s[28:29], s[26:27]
	v_cndmask_b32_e32 v58, v217, v58, vcc
	v_cmp_lt_i32_e32 vcc, 16, v219
	v_cmp_gt_i32_e64 s[22:23], 43, v219
	s_and_b64 s[24:25], s[26:27], s[24:25]
	v_cndmask_b32_e32 v59, v217, v59, vcc
	v_cmp_lt_i32_e32 vcc, 17, v219
	v_cmp_gt_i32_e64 s[20:21], 42, v219
	s_and_b64 s[22:23], s[24:25], s[22:23]
	v_cndmask_b32_e32 v60, v217, v60, vcc
	v_cmp_lt_i32_e32 vcc, 18, v219
	v_cmp_gt_i32_e64 s[18:19], 41, v219
	s_and_b64 s[20:21], s[22:23], s[20:21]
	v_cndmask_b32_e32 v61, v217, v61, vcc
	v_cmp_lt_i32_e32 vcc, 23, v219
	v_cmp_gt_i32_e64 s[14:15], 40, v219
	s_and_b64 s[18:19], s[20:21], s[18:19]
	v_cndmask_b32_e32 v62, v217, v62, vcc
	v_cmp_lt_i32_e32 vcc, 24, v219
	v_cmp_gt_i32_e64 s[12:13], 35, v219
	s_and_b64 s[14:15], s[18:19], s[14:15]
	v_cndmask_b32_e32 v63, v217, v63, vcc
	v_cmp_lt_i32_e32 vcc, 25, v219
	v_cmp_gt_i32_e64 s[10:11], 34, v219
	s_and_b64 s[12:13], s[14:15], s[12:13]
	v_cndmask_b32_e64 v51, v51, v217, s[8:9]
	v_cndmask_b32_e32 v64, v217, v64, vcc
	v_cmp_lt_i32_e32 vcc, 26, v219
	v_cmp_gt_i32_e64 s[8:9], 33, v219
	s_and_b64 s[10:11], s[12:13], s[10:11]
	v_cndmask_b32_e32 v1, v217, v65, vcc
	v_cmp_gt_i32_e32 vcc, 32, v219
	s_and_b64 s[8:9], s[10:11], s[8:9]
	s_and_b64 vcc, s[8:9], vcc
	v_cndmask_b32_e64 v49, v49, v217, s[40:41]
	v_cndmask_b32_e64 v48, v48, v217, s[38:39]
	v_cndmask_b32_e64 v47, v47, v217, s[36:37]
	v_cndmask_b32_e64 v46, v46, v217, s[34:35]
	v_cndmask_b32_e64 v45, v45, v217, s[30:31]
	v_cndmask_b32_e64 v44, v44, v217, s[28:29]
	v_cndmask_b32_e64 v43, v43, v217, s[26:27]
	v_cndmask_b32_e64 v42, v42, v217, s[24:25]
	v_cndmask_b32_e64 v41, v41, v217, s[22:23]
	v_cndmask_b32_e64 v40, v40, v217, s[20:21]
	v_cndmask_b32_e64 v39, v39, v217, s[18:19]
	v_cndmask_b32_e64 v38, v38, v217, s[14:15]
	v_cndmask_b32_e64 v37, v37, v217, s[12:13]
	v_cndmask_b32_e64 v36, v36, v217, s[10:11]
	v_cndmask_b32_e64 v35, v35, v217, s[8:9]
	v_cndmask_b32_e32 v65, v65, v1, vcc
	v_cndmask_b32_e32 v34, v34, v217, vcc
